# phase-7 workgroup entry stagger window shortened (s_sleep 8 -> 5 per step)
# baseline (speedup 1.0000x reference)
; __global__ void __launch_bounds__(512, 2) trunk_fwd(Params p) {
;     ...
;         for (int rep = 0; rep < NREP(7); ++rep) if (PHM & (1u << 7)) { PH_BEGIN
;             const float* gw_s = kp->in[13] + (size_t)lq * 4 * 128 * 128; const float* gb_s = kp->in[14] + (size_t)lq * 4 * 128;
;             const h16* z = WSP(h16, W_Z); h16* cat = WSP(h16, W_CAT); h16* cats = WSP(h16, W_CATS);
;             const int fr = lane & 15, g4 = lane >> 4, q_ = fr >> 2, p_ = fr & 3;
;             for (int item = (bid + G - (1204 % G)) % G; item < 1024 + 128; item += G) {
;                 const bool samp = item >= 1024; const int head = item & 3; const int ci = samp ? (item - 1024) >> 2 : item >> 2;
;                 const int R0 = samp ? MP + ci * 32 : ci * 128, L = samp ? 32 : 128;
;                 __syncthreads();
.Lstag7_loop:
	s_sleep 5
	s_sub_u32 s100, s100, 1
	s_cmp_lg_u32 s100, 0
	s_cbranch_scc1 .Lstag7_loop
